# lever 2 (epilogue de-serialisation) on the GLU GEMM epilogue: bias quads loaded once, 16 activation quads prefetched in two batches, counted vmcnt instead of a 16-step load-wait ladder
# speedup vs baseline: 1.0039x; 1.0039x over previous
.LBB0_735:
	s_add_i32 s20, s24, 0x100
	s_and_b64 s[18:19], s[18:19], exec
	s_cselect_b32 s19, 0, s20
	s_cselect_b32 s18, 0, 0
	s_add_u32 s20, s12, s19
	s_addc_u32 s21, s13, s18
	s_add_i32 s45, 0, 0x10000
	s_add_u32 s22, s8, s19
	s_addc_u32 s23, s9, s18
	s_add_i32 s48, 0, 0x14000
	s_add_u32 s26, s14, s24
	v_add_u32_e32 v152, s45, v138
	v_add_u32_e32 v168, s48, v138
	s_addc_u32 s27, s15, 0
	s_add_i32 s44, s45, s2
	ds_read_b128 v[140:143], v152
	ds_read_b128 v[144:147], v152 offset:1024
	ds_read_b128 v[148:151], v152 offset:2048
	ds_read_b128 v[152:155], v152 offset:3072
	ds_read_b128 v[156:159], v168
	ds_read_b128 v[160:163], v168 offset:1024
	ds_read_b128 v[164:167], v168 offset:2048
	ds_read_b128 v[168:171], v168 offset:3072
	s_add_i32 m0, s28, 0xc000
	s_add_i32 s56, s28, 0xe000
	s_add_i32 s39, s44, 0x2000
	s_add_u32 s24, s22, s6
	s_addc_u32 s25, s23, s7
	s_add_i32 s41, s48, s2
	s_add_i32 s40, s41, 0x2000
	s_add_i32 s38, 0, 0x18000
	s_add_i32 s37, 0, 0x1c000
	s_add_u32 s18, s20, s6
	s_addc_u32 s19, s21, s7
	s_add_i32 s36, s38, s2
	s_add_i32 s48, s37, s2
	s_add_i32 s49, s36, 0x2000
	s_add_i32 s45, s48, 0x2000
	v_lshl_add_u64 v[188:189], s[26:27], 0, v[134:135]
	v_lshl_add_u64 v[188:189], v[188:189], 0, s[68:69]
	ds_read_b128 v[172:175], v139
	ds_read_b128 v[176:179], v139 offset:1024
	ds_read_b128 v[180:183], v139 offset:2048
	ds_read_b128 v[184:187], v139 offset:3072
	ds_read_b128 v[204:207], v139 offset:4096
	ds_read_b128 v[208:211], v139 offset:5120
	ds_read_b128 v[212:215], v139 offset:6144
	ds_read_b128 v[216:219], v139 offset:7168
	global_load_lds_dwordx4 v[188:189], off
	v_lshl_add_u64 v[188:189], s[26:27], 0, v[132:133]
	v_lshl_add_u64 v[188:189], v[188:189], 0, s[68:69]
	s_mov_b32 m0, s56
	s_nop 0
	global_load_lds_dwordx4 v[188:189], off
	s_waitcnt vmcnt(8)
	s_waitcnt lgkmcnt(0)
	s_barrier
	s_setprio 1
	s_waitcnt lgkmcnt(0)
	v_mfma_f32_16x16x32_bf16 v[126:129], v[140:143], v[172:175], v[126:129]
	v_mfma_f32_16x16x32_bf16 v[122:125], v[148:151], v[172:175], v[122:125]
	v_mfma_f32_16x16x32_bf16 v[110:113], v[140:143], v[180:183], v[110:113]
	v_mfma_f32_16x16x32_bf16 v[106:109], v[148:151], v[180:183], v[106:109]
	v_mfma_f32_16x16x32_bf16 v[94:97], v[140:143], v[204:207], v[94:97]
	v_mfma_f32_16x16x32_bf16 v[90:93], v[148:151], v[204:207], v[90:93]
	v_mfma_f32_16x16x32_bf16 v[78:81], v[140:143], v[212:215], v[78:81]
	v_mfma_f32_16x16x32_bf16 v[74:77], v[148:151], v[212:215], v[74:77]
	v_mfma_f32_16x16x32_bf16 v[126:129], v[144:147], v[176:179], v[126:129]
	v_mfma_f32_16x16x32_bf16 v[122:125], v[152:155], v[176:179], v[122:125]
	v_mfma_f32_16x16x32_bf16 v[110:113], v[144:147], v[184:187], v[110:113]
	v_mfma_f32_16x16x32_bf16 v[106:109], v[152:155], v[184:187], v[106:109]
	v_mfma_f32_16x16x32_bf16 v[94:97], v[144:147], v[208:211], v[94:97]
	v_mfma_f32_16x16x32_bf16 v[90:93], v[152:155], v[208:211], v[90:93]
	v_mfma_f32_16x16x32_bf16 v[78:81], v[144:147], v[216:219], v[78:81]
	v_mfma_f32_16x16x32_bf16 v[74:77], v[152:155], v[216:219], v[74:77]
	s_setprio 0
	s_setprio 1
	v_mfma_f32_16x16x32_bf16 v[118:121], v[156:159], v[172:175], v[118:121]
	v_mfma_f32_16x16x32_bf16 v[114:117], v[164:167], v[172:175], v[114:117]
	v_mfma_f32_16x16x32_bf16 v[102:105], v[156:159], v[180:183], v[102:105]
	v_mfma_f32_16x16x32_bf16 v[98:101], v[164:167], v[180:183], v[98:101]
	v_mfma_f32_16x16x32_bf16 v[86:89], v[156:159], v[204:207], v[86:89]
	v_mfma_f32_16x16x32_bf16 v[82:85], v[164:167], v[204:207], v[82:85]
	v_mfma_f32_16x16x32_bf16 v[70:73], v[156:159], v[212:215], v[70:73]
	v_mfma_f32_16x16x32_bf16 v[66:69], v[164:167], v[212:215], v[66:69]
	v_mfma_f32_16x16x32_bf16 v[118:121], v[160:163], v[176:179], v[118:121]
	v_mfma_f32_16x16x32_bf16 v[114:117], v[168:171], v[176:179], v[114:117]
	v_mfma_f32_16x16x32_bf16 v[102:105], v[160:163], v[184:187], v[102:105]
	v_mfma_f32_16x16x32_bf16 v[98:101], v[168:171], v[184:187], v[98:101]
	v_mfma_f32_16x16x32_bf16 v[86:89], v[160:163], v[208:211], v[86:89]
	v_mfma_f32_16x16x32_bf16 v[82:85], v[168:171], v[208:211], v[82:85]
	v_mfma_f32_16x16x32_bf16 v[70:73], v[160:163], v[216:219], v[70:73]
	v_mfma_f32_16x16x32_bf16 v[66:69], v[168:171], v[216:219], v[66:69]
	s_setprio 0
	s_barrier
	s_mov_b32 m0, s44
	v_lshl_add_u64 v[188:189], s[22:23], 0, v[190:191]
	ds_read_b128 v[172:175], v139 offset:16384
	ds_read_b128 v[176:179], v139 offset:17408
	ds_read_b128 v[180:183], v139 offset:18432
	ds_read_b128 v[184:187], v139 offset:19456
	ds_read_b128 v[204:207], v139 offset:20480
	ds_read_b128 v[208:211], v139 offset:21504
	ds_read_b128 v[212:215], v139 offset:22528
	ds_read_b128 v[216:219], v139 offset:23552
	global_load_lds_dwordx4 v[188:189], off
	v_lshl_add_u64 v[220:221], s[22:23], 0, v[130:131]
	s_mov_b32 m0, s39
	v_lshl_add_u64 v[230:231], s[24:25], 0, v[190:191]
	global_load_lds_dwordx4 v[220:221], off
	s_mov_b32 m0, s41
	v_lshl_add_u64 v[232:233], s[24:25], 0, v[130:131]
	global_load_lds_dwordx4 v[230:231], off
	s_mov_b32 m0, s40
	v_lshl_add_u64 v[234:235], s[20:21], 0, v[134:135]
	global_load_lds_dwordx4 v[232:233], off
	s_mov_b32 m0, s28
	v_lshl_add_u64 v[236:237], s[20:21], 0, v[132:133]
	global_load_lds_dwordx4 v[234:235], off
	s_mov_b32 m0, s29
	s_nop 0
	global_load_lds_dwordx4 v[236:237], off
	s_waitcnt vmcnt(8)
	s_waitcnt lgkmcnt(0)
	s_barrier
	s_setprio 1
	s_waitcnt lgkmcnt(0)
	v_mfma_f32_16x16x32_bf16 v[62:65], v[140:143], v[172:175], v[62:65]
	v_mfma_f32_16x16x32_bf16 v[58:61], v[148:151], v[172:175], v[58:61]
	v_mfma_f32_16x16x32_bf16 v[46:49], v[140:143], v[180:183], v[46:49]
	v_mfma_f32_16x16x32_bf16 v[42:45], v[148:151], v[180:183], v[42:45]
	v_mfma_f32_16x16x32_bf16 v[30:33], v[140:143], v[204:207], v[30:33]
	v_mfma_f32_16x16x32_bf16 v[26:29], v[148:151], v[204:207], v[26:29]
	v_mfma_f32_16x16x32_bf16 v[14:17], v[140:143], v[212:215], v[14:17]
	v_mfma_f32_16x16x32_bf16 v[10:13], v[148:151], v[212:215], v[10:13]
	v_mfma_f32_16x16x32_bf16 v[62:65], v[144:147], v[176:179], v[62:65]
	v_mfma_f32_16x16x32_bf16 v[58:61], v[152:155], v[176:179], v[58:61]
	v_mfma_f32_16x16x32_bf16 v[46:49], v[144:147], v[184:187], v[46:49]
	v_mfma_f32_16x16x32_bf16 v[42:45], v[152:155], v[184:187], v[42:45]
	v_mfma_f32_16x16x32_bf16 v[30:33], v[144:147], v[208:211], v[30:33]
	v_mfma_f32_16x16x32_bf16 v[26:29], v[152:155], v[208:211], v[26:29]
	v_mfma_f32_16x16x32_bf16 v[14:17], v[144:147], v[216:219], v[14:17]
	v_mfma_f32_16x16x32_bf16 v[10:13], v[152:155], v[216:219], v[10:13]
	s_setprio 0
	s_setprio 1
	v_mfma_f32_16x16x32_bf16 v[54:57], v[156:159], v[172:175], v[54:57]
	v_mfma_f32_16x16x32_bf16 v[50:53], v[164:167], v[172:175], v[50:53]
	v_mfma_f32_16x16x32_bf16 v[38:41], v[156:159], v[180:183], v[38:41]
	v_mfma_f32_16x16x32_bf16 v[34:37], v[164:167], v[180:183], v[34:37]
	v_mfma_f32_16x16x32_bf16 v[22:25], v[156:159], v[204:207], v[22:25]
	v_mfma_f32_16x16x32_bf16 v[18:21], v[164:167], v[204:207], v[18:21]
	v_mfma_f32_16x16x32_bf16 v[6:9], v[156:159], v[212:215], v[6:9]
	v_mfma_f32_16x16x32_bf16 v[2:5], v[164:167], v[212:215], v[2:5]
	v_mfma_f32_16x16x32_bf16 v[54:57], v[160:163], v[176:179], v[54:57]
	v_mfma_f32_16x16x32_bf16 v[50:53], v[168:171], v[176:179], v[50:53]
	v_mfma_f32_16x16x32_bf16 v[38:41], v[160:163], v[184:187], v[38:41]
	v_mfma_f32_16x16x32_bf16 v[34:37], v[168:171], v[184:187], v[34:37]
	v_mfma_f32_16x16x32_bf16 v[22:25], v[160:163], v[208:211], v[22:25]
	v_mfma_f32_16x16x32_bf16 v[18:21], v[168:171], v[208:211], v[18:21]
	v_mfma_f32_16x16x32_bf16 v[6:9], v[160:163], v[216:219], v[6:9]
	v_mfma_f32_16x16x32_bf16 v[2:5], v[168:171], v[216:219], v[2:5]
	s_setprio 0
	s_barrier
	v_add_u32_e32 v152, s38, v138
	v_add_u32_e32 v168, s37, v138
	ds_read_b128 v[140:143], v152
	ds_read_b128 v[144:147], v152 offset:1024
	ds_read_b128 v[148:151], v152 offset:2048
	ds_read_b128 v[152:155], v152 offset:3072
	ds_read_b128 v[156:159], v168
	ds_read_b128 v[160:163], v168 offset:1024
	ds_read_b128 v[164:167], v168 offset:2048
	ds_read_b128 v[168:171], v168 offset:3072
	s_mov_b32 m0, s30
	v_lshl_add_u64 v[238:239], s[18:19], 0, v[134:135]
	ds_read_b128 v[172:175], v139 offset:32768
	ds_read_b128 v[176:179], v139 offset:33792
	ds_read_b128 v[180:183], v139 offset:34816
	ds_read_b128 v[184:187], v139 offset:35840
	ds_read_b128 v[204:207], v139 offset:36864
	ds_read_b128 v[208:211], v139 offset:37888
	ds_read_b128 v[212:215], v139 offset:38912
	ds_read_b128 v[216:219], v139 offset:39936
	global_load_lds_dwordx4 v[238:239], off
	v_lshl_add_u64 v[238:239], s[18:19], 0, v[132:133]
	s_mov_b32 m0, s31
	s_nop 0
	global_load_lds_dwordx4 v[238:239], off
	s_waitcnt vmcnt(8)
	s_waitcnt lgkmcnt(0)
	s_barrier
	s_setprio 1
	s_waitcnt lgkmcnt(0)
	v_mfma_f32_16x16x32_bf16 v[126:129], v[140:143], v[172:175], v[126:129]
	v_mfma_f32_16x16x32_bf16 v[122:125], v[148:151], v[172:175], v[122:125]
	v_mfma_f32_16x16x32_bf16 v[110:113], v[140:143], v[180:183], v[110:113]
	v_mfma_f32_16x16x32_bf16 v[106:109], v[148:151], v[180:183], v[106:109]
	v_mfma_f32_16x16x32_bf16 v[94:97], v[140:143], v[204:207], v[94:97]
	v_mfma_f32_16x16x32_bf16 v[90:93], v[148:151], v[204:207], v[90:93]
	v_mfma_f32_16x16x32_bf16 v[78:81], v[140:143], v[212:215], v[78:81]
	v_mfma_f32_16x16x32_bf16 v[74:77], v[148:151], v[212:215], v[74:77]
	v_mfma_f32_16x16x32_bf16 v[126:129], v[144:147], v[176:179], v[126:129]
	v_mfma_f32_16x16x32_bf16 v[122:125], v[152:155], v[176:179], v[122:125]
	v_mfma_f32_16x16x32_bf16 v[110:113], v[144:147], v[184:187], v[110:113]
	v_mfma_f32_16x16x32_bf16 v[106:109], v[152:155], v[184:187], v[106:109]
	v_mfma_f32_16x16x32_bf16 v[94:97], v[144:147], v[208:211], v[94:97]
	v_mfma_f32_16x16x32_bf16 v[90:93], v[152:155], v[208:211], v[90:93]
	v_mfma_f32_16x16x32_bf16 v[78:81], v[144:147], v[216:219], v[78:81]
	v_mfma_f32_16x16x32_bf16 v[74:77], v[152:155], v[216:219], v[74:77]
	s_setprio 0
	s_setprio 1
	v_mfma_f32_16x16x32_bf16 v[118:121], v[156:159], v[172:175], v[118:121]
	v_mfma_f32_16x16x32_bf16 v[114:117], v[164:167], v[172:175], v[114:117]
	v_mfma_f32_16x16x32_bf16 v[102:105], v[156:159], v[180:183], v[102:105]
	v_mfma_f32_16x16x32_bf16 v[98:101], v[164:167], v[180:183], v[98:101]
	v_mfma_f32_16x16x32_bf16 v[86:89], v[156:159], v[204:207], v[86:89]
	v_mfma_f32_16x16x32_bf16 v[82:85], v[164:167], v[204:207], v[82:85]
	v_mfma_f32_16x16x32_bf16 v[70:73], v[156:159], v[212:215], v[70:73]
	v_mfma_f32_16x16x32_bf16 v[66:69], v[164:167], v[212:215], v[66:69]
	v_mfma_f32_16x16x32_bf16 v[118:121], v[160:163], v[176:179], v[118:121]
	v_mfma_f32_16x16x32_bf16 v[114:117], v[168:171], v[176:179], v[114:117]
	v_mfma_f32_16x16x32_bf16 v[102:105], v[160:163], v[184:187], v[102:105]
	v_mfma_f32_16x16x32_bf16 v[98:101], v[168:171], v[184:187], v[98:101]
	v_mfma_f32_16x16x32_bf16 v[86:89], v[160:163], v[208:211], v[86:89]
	v_mfma_f32_16x16x32_bf16 v[82:85], v[168:171], v[208:211], v[82:85]
	v_mfma_f32_16x16x32_bf16 v[70:73], v[160:163], v[216:219], v[70:73]
	v_mfma_f32_16x16x32_bf16 v[66:69], v[168:171], v[216:219], v[66:69]
	s_setprio 0
	s_barrier
	s_mov_b32 m0, s36
	v_lshl_add_u64 v[188:189], v[188:189], 0, s[68:69]
	ds_read_b128 v[172:175], v139 offset:49152
	ds_read_b128 v[176:179], v139 offset:50176
	ds_read_b128 v[180:183], v139 offset:51200
	ds_read_b128 v[184:187], v139 offset:52224
	ds_read_b128 v[204:207], v139 offset:53248
	ds_read_b128 v[208:211], v139 offset:54272
	ds_read_b128 v[212:215], v139 offset:55296
	ds_read_b128 v[216:219], v139 offset:56320
	global_load_lds_dwordx4 v[188:189], off
	v_lshl_add_u64 v[188:189], v[220:221], 0, s[68:69]
	s_mov_b32 m0, s49
	s_nop 0
	global_load_lds_dwordx4 v[188:189], off
	v_lshl_add_u64 v[188:189], v[230:231], 0, s[68:69]
	s_mov_b32 m0, s48
	s_nop 0
	global_load_lds_dwordx4 v[188:189], off
	v_lshl_add_u64 v[188:189], v[232:233], 0, s[68:69]
	s_mov_b32 m0, s45
	s_nop 0
	global_load_lds_dwordx4 v[188:189], off
	v_lshl_add_u64 v[188:189], v[234:235], 0, s[68:69]
	s_mov_b32 m0, s34
	s_nop 0
	global_load_lds_dwordx4 v[188:189], off
	v_lshl_add_u64 v[188:189], v[236:237], 0, s[68:69]
	s_mov_b32 m0, s35
	s_nop 0
	global_load_lds_dwordx4 v[188:189], off
	s_waitcnt vmcnt(8)
	s_waitcnt lgkmcnt(0)
	s_barrier
	s_setprio 1
	s_waitcnt lgkmcnt(0)
	v_mfma_f32_16x16x32_bf16 v[62:65], v[140:143], v[172:175], v[62:65]
	v_mfma_f32_16x16x32_bf16 v[58:61], v[148:151], v[172:175], v[58:61]
	v_mfma_f32_16x16x32_bf16 v[46:49], v[140:143], v[180:183], v[46:49]
	v_mfma_f32_16x16x32_bf16 v[42:45], v[148:151], v[180:183], v[42:45]
	v_mfma_f32_16x16x32_bf16 v[30:33], v[140:143], v[204:207], v[30:33]
	v_mfma_f32_16x16x32_bf16 v[26:29], v[148:151], v[204:207], v[26:29]
	v_mfma_f32_16x16x32_bf16 v[14:17], v[140:143], v[212:215], v[14:17]
	v_mfma_f32_16x16x32_bf16 v[10:13], v[148:151], v[212:215], v[10:13]
	v_mfma_f32_16x16x32_bf16 v[62:65], v[144:147], v[176:179], v[62:65]
	v_mfma_f32_16x16x32_bf16 v[58:61], v[152:155], v[176:179], v[58:61]
	v_mfma_f32_16x16x32_bf16 v[46:49], v[144:147], v[184:187], v[46:49]
	v_mfma_f32_16x16x32_bf16 v[42:45], v[152:155], v[184:187], v[42:45]
	v_mfma_f32_16x16x32_bf16 v[30:33], v[144:147], v[208:211], v[30:33]
	v_mfma_f32_16x16x32_bf16 v[26:29], v[152:155], v[208:211], v[26:29]
	v_mfma_f32_16x16x32_bf16 v[14:17], v[144:147], v[216:219], v[14:17]
	v_mfma_f32_16x16x32_bf16 v[10:13], v[152:155], v[216:219], v[10:13]
	s_setprio 0
	s_setprio 1
	v_mfma_f32_16x16x32_bf16 v[54:57], v[156:159], v[172:175], v[54:57]
	v_mfma_f32_16x16x32_bf16 v[50:53], v[164:167], v[172:175], v[50:53]
	v_mfma_f32_16x16x32_bf16 v[38:41], v[156:159], v[180:183], v[38:41]
	v_mfma_f32_16x16x32_bf16 v[34:37], v[164:167], v[180:183], v[34:37]
	v_mfma_f32_16x16x32_bf16 v[22:25], v[156:159], v[204:207], v[22:25]
	v_mfma_f32_16x16x32_bf16 v[18:21], v[164:167], v[204:207], v[18:21]
	v_mfma_f32_16x16x32_bf16 v[6:9], v[156:159], v[212:215], v[6:9]
	v_mfma_f32_16x16x32_bf16 v[2:5], v[164:167], v[212:215], v[2:5]
	v_mfma_f32_16x16x32_bf16 v[54:57], v[160:163], v[176:179], v[54:57]
	v_mfma_f32_16x16x32_bf16 v[50:53], v[168:171], v[176:179], v[50:53]
	v_mfma_f32_16x16x32_bf16 v[38:41], v[160:163], v[184:187], v[38:41]
	v_mfma_f32_16x16x32_bf16 v[34:37], v[168:171], v[184:187], v[34:37]
	v_mfma_f32_16x16x32_bf16 v[22:25], v[160:163], v[208:211], v[22:25]
	v_mfma_f32_16x16x32_bf16 v[18:21], v[168:171], v[208:211], v[18:21]
	v_mfma_f32_16x16x32_bf16 v[6:9], v[160:163], v[216:219], v[6:9]
	v_mfma_f32_16x16x32_bf16 v[2:5], v[168:171], v[216:219], v[2:5]
	s_setprio 0
	s_barrier
	s_andn2_b64 vcc, exec, s[16:17]
	s_mov_b64 s[18:19], -1
	s_mov_b64 s[16:17], 0
	s_movk_i32 s24, 0x100
	s_cbranch_vccz .LBB0_735
	s_add_u32 s6, s54, 0xf226000
	s_addc_u32 s7, s55, 0
	s_lshl_b32 s2, s92, 8
	v_lshl_add_u32 v134, s3, 8, v137
	s_ashr_i32 s3, s2, 31
	s_lshl_b64 s[2:3], s[2:3], 2
	v_lshl_add_u32 v130, v136, 3, s33
	v_ashrrev_i32_e32 v135, 31, v134
	v_lshlrev_b64 v[132:133], 9, v[134:135]
	v_ashrrev_i32_e32 v131, 31, v130
	s_add_u32 s2, s10, s2
	v_lshl_add_u64 v[136:137], s[4:5], 0, v[132:133]
	v_lshlrev_b64 v[132:133], 1, v[130:131]
	s_addc_u32 s3, s11, s3
	v_lshl_add_u64 v[148:149], v[136:137], 0, v[132:133]
	v_lshl_add_u64 v[130:131], v[130:131], 2, s[2:3]
	v_lshlrev_b64 v[150:151], 11, v[134:135]
	v_lshl_add_u64 v[150:151], s[6:7], 0, v[150:151]
	v_lshl_add_u64 v[150:151], v[150:151], 0, v[132:133]
	s_cmpk_lt_u32 s0, 0x100
	s_movk_i32 s93, 0x60
	global_load_dwordx4 v[132:135], v[130:131], off
	global_load_dwordx4 v[136:139], v[130:131], off offset:16
	global_load_dwordx4 v[140:143], v[130:131], off offset:512
	global_load_dwordx4 v[144:147], v[130:131], off offset:528
	global_load_dwordx4 v[152:155], v[148:149], off
	global_load_dwordx4 v[156:159], v[148:149], off offset:256
	v_add_co_u32_e32 v148, vcc, 0x2000, v148
	s_nop 1
	v_addc_co_u32_e32 v149, vcc, 0, v149, vcc
	global_load_dwordx4 v[160:163], v[148:149], off
	global_load_dwordx4 v[164:167], v[148:149], off offset:256
	v_add_co_u32_e32 v148, vcc, 0x2000, v148
	s_nop 1
	v_addc_co_u32_e32 v149, vcc, 0, v149, vcc
	global_load_dwordx4 v[168:171], v[148:149], off
	global_load_dwordx4 v[172:175], v[148:149], off offset:256
	v_add_co_u32_e32 v148, vcc, 0x2000, v148
	s_nop 1
	v_addc_co_u32_e32 v149, vcc, 0, v149, vcc
	global_load_dwordx4 v[176:179], v[148:149], off
	global_load_dwordx4 v[180:183], v[148:149], off offset:256
	v_add_co_u32_e32 v148, vcc, 0xa000, v148
	s_nop 1
	v_addc_co_u32_e32 v149, vcc, 0, v149, vcc
	s_waitcnt vmcnt(7)
	v_pk_add_f32 v[128:129], v[128:129], v[134:135]
	v_pk_add_f32 v[126:127], v[126:127], v[132:133]
	v_pk_add_f32 v[124:125], v[124:125], v[138:139]
	v_pk_add_f32 v[122:123], v[122:123], v[136:137]
	v_mul_f32_e32 v126, 0xbfb8aa3b, v126
	v_mul_f32_e32 v122, 0xbfb8aa3b, v122
	v_mul_f32_e32 v127, 0xbfb8aa3b, v127
	v_mul_f32_e32 v123, 0xbfb8aa3b, v123
	v_mul_f32_e32 v128, 0xbfb8aa3b, v128
	v_mul_f32_e32 v124, 0xbfb8aa3b, v124
	v_mul_f32_e32 v129, 0xbfb8aa3b, v129
	v_mul_f32_e32 v125, 0xbfb8aa3b, v125
	v_exp_f32_e32 v126, v126
	v_exp_f32_e32 v122, v122
	v_exp_f32_e32 v127, v127
	v_exp_f32_e32 v123, v123
	v_exp_f32_e32 v128, v128
	v_exp_f32_e32 v124, v124
	v_exp_f32_e32 v129, v129
	v_exp_f32_e32 v125, v125
	v_and_b32_e32 v185, 0xffff0000, v152
	v_lshlrev_b32_e32 v184, 16, v152
	v_and_b32_e32 v187, 0xffff0000, v153
	v_lshlrev_b32_e32 v186, 16, v153
	v_and_b32_e32 v189, 0xffff0000, v154
	v_lshlrev_b32_e32 v188, 16, v154
	v_and_b32_e32 v131, 0xffff0000, v155
	v_lshlrev_b32_e32 v130, 16, v155
	v_add_f32_e32 v126, 1.0, v126
	v_add_f32_e32 v122, 1.0, v122
	v_add_f32_e32 v127, 1.0, v127
	v_add_f32_e32 v123, 1.0, v123
	v_add_f32_e32 v128, 1.0, v128
	v_add_f32_e32 v124, 1.0, v124
	v_add_f32_e32 v129, 1.0, v129
	v_add_f32_e32 v125, 1.0, v125
	v_rcp_f32_e32 v126, v126
	v_rcp_f32_e32 v122, v122
	v_rcp_f32_e32 v127, v127
	v_rcp_f32_e32 v123, v123
	v_rcp_f32_e32 v128, v128
	v_rcp_f32_e32 v124, v124
	v_rcp_f32_e32 v129, v129
	v_rcp_f32_e32 v125, v125
	v_pk_mul_f32 v[126:127], v[126:127], v[184:185]
	v_pk_mul_f32 v[128:129], v[128:129], v[186:187]
	v_pk_mul_f32 v[122:123], v[122:123], v[188:189]
	v_pk_mul_f32 v[124:125], v[124:125], v[130:131]
	v_cvt_pk_bf16_f32 v126, v126, v127
	v_cvt_pk_bf16_f32 v127, v128, v129
	v_cvt_pk_bf16_f32 v128, v122, v123
	v_cvt_pk_bf16_f32 v129, v124, v125
	global_store_dwordx4 v[150:151], v[126:129], off offset:512
	s_waitcnt vmcnt(7)
	v_pk_add_f32 v[120:121], v[120:121], v[142:143]
	v_pk_add_f32 v[118:119], v[118:119], v[140:141]
	v_pk_add_f32 v[116:117], v[116:117], v[146:147]
	v_pk_add_f32 v[114:115], v[114:115], v[144:145]
	v_mul_f32_e32 v118, 0xbfb8aa3b, v118
	v_mul_f32_e32 v114, 0xbfb8aa3b, v114
	v_mul_f32_e32 v119, 0xbfb8aa3b, v119
	v_mul_f32_e32 v115, 0xbfb8aa3b, v115
	v_mul_f32_e32 v120, 0xbfb8aa3b, v120
	v_mul_f32_e32 v116, 0xbfb8aa3b, v116
	v_mul_f32_e32 v121, 0xbfb8aa3b, v121
	v_mul_f32_e32 v117, 0xbfb8aa3b, v117
	v_exp_f32_e32 v118, v118
	v_exp_f32_e32 v114, v114
	v_exp_f32_e32 v119, v119
	v_exp_f32_e32 v115, v115
	v_exp_f32_e32 v120, v120
	v_exp_f32_e32 v116, v116
	v_exp_f32_e32 v121, v121
	v_exp_f32_e32 v117, v117
	v_and_b32_e32 v185, 0xffff0000, v156
	v_lshlrev_b32_e32 v184, 16, v156
	v_and_b32_e32 v187, 0xffff0000, v157
	v_lshlrev_b32_e32 v186, 16, v157
	v_and_b32_e32 v189, 0xffff0000, v158
	v_lshlrev_b32_e32 v188, 16, v158
	v_and_b32_e32 v131, 0xffff0000, v159
	v_lshlrev_b32_e32 v130, 16, v159
	v_add_f32_e32 v118, 1.0, v118
	v_add_f32_e32 v114, 1.0, v114
	v_add_f32_e32 v119, 1.0, v119
	v_add_f32_e32 v115, 1.0, v115
	v_add_f32_e32 v120, 1.0, v120
	v_add_f32_e32 v116, 1.0, v116
	v_add_f32_e32 v121, 1.0, v121
	v_add_f32_e32 v117, 1.0, v117
	v_rcp_f32_e32 v118, v118
	v_rcp_f32_e32 v114, v114
	v_rcp_f32_e32 v119, v119
	v_rcp_f32_e32 v115, v115
	v_rcp_f32_e32 v120, v120
	v_rcp_f32_e32 v116, v116
	v_rcp_f32_e32 v121, v121
	v_rcp_f32_e32 v117, v117
	v_pk_mul_f32 v[118:119], v[118:119], v[184:185]
	v_pk_mul_f32 v[120:121], v[120:121], v[186:187]
	v_pk_mul_f32 v[114:115], v[114:115], v[188:189]
	v_pk_mul_f32 v[116:117], v[116:117], v[130:131]
	v_cvt_pk_bf16_f32 v118, v118, v119
	v_cvt_pk_bf16_f32 v119, v120, v121
	v_cvt_pk_bf16_f32 v120, v114, v115
	v_cvt_pk_bf16_f32 v121, v116, v117
	global_store_dwordx4 v[150:151], v[118:121], off offset:768
	v_add_co_u32_e32 v150, vcc, 0x8000, v150
	s_nop 1
	v_addc_co_u32_e32 v151, vcc, 0, v151, vcc
	s_waitcnt vmcnt(7)
	v_pk_add_f32 v[112:113], v[112:113], v[134:135]
	v_pk_add_f32 v[110:111], v[110:111], v[132:133]
	v_pk_add_f32 v[108:109], v[108:109], v[138:139]
	v_pk_add_f32 v[106:107], v[106:107], v[136:137]
	v_mul_f32_e32 v110, 0xbfb8aa3b, v110
	v_mul_f32_e32 v106, 0xbfb8aa3b, v106
	v_mul_f32_e32 v111, 0xbfb8aa3b, v111
	v_mul_f32_e32 v107, 0xbfb8aa3b, v107
	v_mul_f32_e32 v112, 0xbfb8aa3b, v112
	v_mul_f32_e32 v108, 0xbfb8aa3b, v108
	v_mul_f32_e32 v113, 0xbfb8aa3b, v113
	v_mul_f32_e32 v109, 0xbfb8aa3b, v109
	v_exp_f32_e32 v110, v110
	v_exp_f32_e32 v106, v106
	v_exp_f32_e32 v111, v111
	v_exp_f32_e32 v107, v107
	v_exp_f32_e32 v112, v112
	v_exp_f32_e32 v108, v108
	v_exp_f32_e32 v113, v113
	v_exp_f32_e32 v109, v109
	v_and_b32_e32 v185, 0xffff0000, v160
	v_lshlrev_b32_e32 v184, 16, v160
	v_and_b32_e32 v187, 0xffff0000, v161
	v_lshlrev_b32_e32 v186, 16, v161
	v_and_b32_e32 v189, 0xffff0000, v162
	v_lshlrev_b32_e32 v188, 16, v162
	v_and_b32_e32 v131, 0xffff0000, v163
	v_lshlrev_b32_e32 v130, 16, v163
	v_add_f32_e32 v110, 1.0, v110
	v_add_f32_e32 v106, 1.0, v106
	v_add_f32_e32 v111, 1.0, v111
	v_add_f32_e32 v107, 1.0, v107
	v_add_f32_e32 v112, 1.0, v112
	v_add_f32_e32 v108, 1.0, v108
	v_add_f32_e32 v113, 1.0, v113
	v_add_f32_e32 v109, 1.0, v109
	v_rcp_f32_e32 v110, v110
	v_rcp_f32_e32 v106, v106
	v_rcp_f32_e32 v111, v111
	v_rcp_f32_e32 v107, v107
	v_rcp_f32_e32 v112, v112
	v_rcp_f32_e32 v108, v108
	v_rcp_f32_e32 v113, v113
	v_rcp_f32_e32 v109, v109
	v_pk_mul_f32 v[110:111], v[110:111], v[184:185]
	v_pk_mul_f32 v[112:113], v[112:113], v[186:187]
	v_pk_mul_f32 v[106:107], v[106:107], v[188:189]
	v_pk_mul_f32 v[108:109], v[108:109], v[130:131]
	v_cvt_pk_bf16_f32 v110, v110, v111
	v_cvt_pk_bf16_f32 v111, v112, v113
	v_cvt_pk_bf16_f32 v112, v106, v107
	v_cvt_pk_bf16_f32 v113, v108, v109
	global_store_dwordx4 v[150:151], v[110:113], off offset:512
	s_waitcnt vmcnt(7)
	v_pk_add_f32 v[104:105], v[104:105], v[142:143]
	v_pk_add_f32 v[102:103], v[102:103], v[140:141]
	v_pk_add_f32 v[100:101], v[100:101], v[146:147]
	v_pk_add_f32 v[98:99], v[98:99], v[144:145]
	v_mul_f32_e32 v102, 0xbfb8aa3b, v102
	v_mul_f32_e32 v98, 0xbfb8aa3b, v98
	v_mul_f32_e32 v103, 0xbfb8aa3b, v103
	v_mul_f32_e32 v99, 0xbfb8aa3b, v99
	v_mul_f32_e32 v104, 0xbfb8aa3b, v104
	v_mul_f32_e32 v100, 0xbfb8aa3b, v100
	v_mul_f32_e32 v105, 0xbfb8aa3b, v105
	v_mul_f32_e32 v101, 0xbfb8aa3b, v101
	v_exp_f32_e32 v102, v102
	v_exp_f32_e32 v98, v98
	v_exp_f32_e32 v103, v103
	v_exp_f32_e32 v99, v99
	v_exp_f32_e32 v104, v104
	v_exp_f32_e32 v100, v100
	v_exp_f32_e32 v105, v105
	v_exp_f32_e32 v101, v101
	v_and_b32_e32 v185, 0xffff0000, v164
	v_lshlrev_b32_e32 v184, 16, v164
	v_and_b32_e32 v187, 0xffff0000, v165
	v_lshlrev_b32_e32 v186, 16, v165
	v_and_b32_e32 v189, 0xffff0000, v166
	v_lshlrev_b32_e32 v188, 16, v166
	v_and_b32_e32 v131, 0xffff0000, v167
	v_lshlrev_b32_e32 v130, 16, v167
	v_add_f32_e32 v102, 1.0, v102
	v_add_f32_e32 v98, 1.0, v98
	v_add_f32_e32 v103, 1.0, v103
	v_add_f32_e32 v99, 1.0, v99
	v_add_f32_e32 v104, 1.0, v104
	v_add_f32_e32 v100, 1.0, v100
	v_add_f32_e32 v105, 1.0, v105
	v_add_f32_e32 v101, 1.0, v101
	v_rcp_f32_e32 v102, v102
	v_rcp_f32_e32 v98, v98
	v_rcp_f32_e32 v103, v103
	v_rcp_f32_e32 v99, v99
	v_rcp_f32_e32 v104, v104
	v_rcp_f32_e32 v100, v100
	v_rcp_f32_e32 v105, v105
	v_rcp_f32_e32 v101, v101
	v_pk_mul_f32 v[102:103], v[102:103], v[184:185]
	v_pk_mul_f32 v[104:105], v[104:105], v[186:187]
	v_pk_mul_f32 v[98:99], v[98:99], v[188:189]
	v_pk_mul_f32 v[100:101], v[100:101], v[130:131]
	v_cvt_pk_bf16_f32 v102, v102, v103
	v_cvt_pk_bf16_f32 v103, v104, v105
	v_cvt_pk_bf16_f32 v104, v98, v99
	v_cvt_pk_bf16_f32 v105, v100, v101
	global_store_dwordx4 v[150:151], v[102:105], off offset:768
	v_add_co_u32_e32 v150, vcc, 0x8000, v150
	s_nop 1
	v_addc_co_u32_e32 v151, vcc, 0, v151, vcc
	s_nop 1
	global_load_dwordx4 v[98:101], v[148:149], off
	global_load_dwordx4 v[102:105], v[148:149], off offset:256
	v_add_co_u32_e32 v148, vcc, 0x2000, v148
	s_nop 1
	v_addc_co_u32_e32 v149, vcc, 0, v149, vcc
	global_load_dwordx4 v[106:109], v[148:149], off
	global_load_dwordx4 v[110:113], v[148:149], off offset:256
	v_add_co_u32_e32 v148, vcc, 0x2000, v148
	s_nop 1
	v_addc_co_u32_e32 v149, vcc, 0, v149, vcc
	global_load_dwordx4 v[114:117], v[148:149], off
	global_load_dwordx4 v[118:121], v[148:149], off offset:256
	v_add_co_u32_e32 v148, vcc, 0x2000, v148
	s_nop 1
	v_addc_co_u32_e32 v149, vcc, 0, v149, vcc
	global_load_dwordx4 v[122:125], v[148:149], off
	global_load_dwordx4 v[126:129], v[148:149], off offset:256
	s_waitcnt vmcnt(15)
	v_pk_add_f32 v[96:97], v[96:97], v[134:135]
	v_pk_add_f32 v[94:95], v[94:95], v[132:133]
	v_pk_add_f32 v[92:93], v[92:93], v[138:139]
	v_pk_add_f32 v[90:91], v[90:91], v[136:137]
	v_mul_f32_e32 v94, 0xbfb8aa3b, v94
	v_mul_f32_e32 v90, 0xbfb8aa3b, v90
	v_mul_f32_e32 v95, 0xbfb8aa3b, v95
	v_mul_f32_e32 v91, 0xbfb8aa3b, v91
	v_mul_f32_e32 v96, 0xbfb8aa3b, v96
	v_mul_f32_e32 v92, 0xbfb8aa3b, v92
	v_mul_f32_e32 v97, 0xbfb8aa3b, v97
	v_mul_f32_e32 v93, 0xbfb8aa3b, v93
	v_exp_f32_e32 v94, v94
	v_exp_f32_e32 v90, v90
	v_exp_f32_e32 v95, v95
	v_exp_f32_e32 v91, v91
	v_exp_f32_e32 v96, v96
	v_exp_f32_e32 v92, v92
	v_exp_f32_e32 v97, v97
	v_exp_f32_e32 v93, v93
	v_and_b32_e32 v185, 0xffff0000, v168
	v_lshlrev_b32_e32 v184, 16, v168
	v_and_b32_e32 v187, 0xffff0000, v169
	v_lshlrev_b32_e32 v186, 16, v169
	v_and_b32_e32 v189, 0xffff0000, v170
	v_lshlrev_b32_e32 v188, 16, v170
	v_and_b32_e32 v131, 0xffff0000, v171
	v_lshlrev_b32_e32 v130, 16, v171
	v_add_f32_e32 v94, 1.0, v94
	v_add_f32_e32 v90, 1.0, v90
	v_add_f32_e32 v95, 1.0, v95
	v_add_f32_e32 v91, 1.0, v91
	v_add_f32_e32 v96, 1.0, v96
	v_add_f32_e32 v92, 1.0, v92
	v_add_f32_e32 v97, 1.0, v97
	v_add_f32_e32 v93, 1.0, v93
	v_rcp_f32_e32 v94, v94
	v_rcp_f32_e32 v90, v90
	v_rcp_f32_e32 v95, v95
	v_rcp_f32_e32 v91, v91
	v_rcp_f32_e32 v96, v96
	v_rcp_f32_e32 v92, v92
	v_rcp_f32_e32 v97, v97
	v_rcp_f32_e32 v93, v93
	v_pk_mul_f32 v[94:95], v[94:95], v[184:185]
	v_pk_mul_f32 v[96:97], v[96:97], v[186:187]
	v_pk_mul_f32 v[90:91], v[90:91], v[188:189]
	v_pk_mul_f32 v[92:93], v[92:93], v[130:131]
	v_cvt_pk_bf16_f32 v94, v94, v95
	v_cvt_pk_bf16_f32 v95, v96, v97
	v_cvt_pk_bf16_f32 v96, v90, v91
	v_cvt_pk_bf16_f32 v97, v92, v93
	global_store_dwordx4 v[150:151], v[94:97], off offset:512
	s_waitcnt vmcnt(15)
	v_pk_add_f32 v[88:89], v[88:89], v[142:143]
	v_pk_add_f32 v[86:87], v[86:87], v[140:141]
	v_pk_add_f32 v[84:85], v[84:85], v[146:147]
	v_pk_add_f32 v[82:83], v[82:83], v[144:145]
	v_mul_f32_e32 v86, 0xbfb8aa3b, v86
	v_mul_f32_e32 v82, 0xbfb8aa3b, v82
	v_mul_f32_e32 v87, 0xbfb8aa3b, v87
	v_mul_f32_e32 v83, 0xbfb8aa3b, v83
	v_mul_f32_e32 v88, 0xbfb8aa3b, v88
	v_mul_f32_e32 v84, 0xbfb8aa3b, v84
	v_mul_f32_e32 v89, 0xbfb8aa3b, v89
	v_mul_f32_e32 v85, 0xbfb8aa3b, v85
	v_exp_f32_e32 v86, v86
	v_exp_f32_e32 v82, v82
	v_exp_f32_e32 v87, v87
	v_exp_f32_e32 v83, v83
	v_exp_f32_e32 v88, v88
	v_exp_f32_e32 v84, v84
	v_exp_f32_e32 v89, v89
	v_exp_f32_e32 v85, v85
	v_and_b32_e32 v185, 0xffff0000, v172
	v_lshlrev_b32_e32 v184, 16, v172
	v_and_b32_e32 v187, 0xffff0000, v173
	v_lshlrev_b32_e32 v186, 16, v173
	v_and_b32_e32 v189, 0xffff0000, v174
	v_lshlrev_b32_e32 v188, 16, v174
	v_and_b32_e32 v131, 0xffff0000, v175
	v_lshlrev_b32_e32 v130, 16, v175
	v_add_f32_e32 v86, 1.0, v86
	v_add_f32_e32 v82, 1.0, v82
	v_add_f32_e32 v87, 1.0, v87
	v_add_f32_e32 v83, 1.0, v83
	v_add_f32_e32 v88, 1.0, v88
	v_add_f32_e32 v84, 1.0, v84
	v_add_f32_e32 v89, 1.0, v89
	v_add_f32_e32 v85, 1.0, v85
	v_rcp_f32_e32 v86, v86
	v_rcp_f32_e32 v82, v82
	v_rcp_f32_e32 v87, v87
	v_rcp_f32_e32 v83, v83
	v_rcp_f32_e32 v88, v88
	v_rcp_f32_e32 v84, v84
	v_rcp_f32_e32 v89, v89
	v_rcp_f32_e32 v85, v85
	v_pk_mul_f32 v[86:87], v[86:87], v[184:185]
	v_pk_mul_f32 v[88:89], v[88:89], v[186:187]
	v_pk_mul_f32 v[82:83], v[82:83], v[188:189]
	v_pk_mul_f32 v[84:85], v[84:85], v[130:131]
	v_cvt_pk_bf16_f32 v86, v86, v87
	v_cvt_pk_bf16_f32 v87, v88, v89
	v_cvt_pk_bf16_f32 v88, v82, v83
	v_cvt_pk_bf16_f32 v89, v84, v85
	global_store_dwordx4 v[150:151], v[86:89], off offset:768
	v_add_co_u32_e32 v150, vcc, 0x8000, v150
	s_nop 1
	v_addc_co_u32_e32 v151, vcc, 0, v151, vcc
	s_waitcnt vmcnt(15)
	v_pk_add_f32 v[80:81], v[80:81], v[134:135]
	v_pk_add_f32 v[78:79], v[78:79], v[132:133]
	v_pk_add_f32 v[76:77], v[76:77], v[138:139]
	v_pk_add_f32 v[74:75], v[74:75], v[136:137]
	v_mul_f32_e32 v78, 0xbfb8aa3b, v78
	v_mul_f32_e32 v74, 0xbfb8aa3b, v74
	v_mul_f32_e32 v79, 0xbfb8aa3b, v79
	v_mul_f32_e32 v75, 0xbfb8aa3b, v75
	v_mul_f32_e32 v80, 0xbfb8aa3b, v80
	v_mul_f32_e32 v76, 0xbfb8aa3b, v76
	v_mul_f32_e32 v81, 0xbfb8aa3b, v81
	v_mul_f32_e32 v77, 0xbfb8aa3b, v77
	v_exp_f32_e32 v78, v78
	v_exp_f32_e32 v74, v74
	v_exp_f32_e32 v79, v79
	v_exp_f32_e32 v75, v75
	v_exp_f32_e32 v80, v80
	v_exp_f32_e32 v76, v76
	v_exp_f32_e32 v81, v81
	v_exp_f32_e32 v77, v77
	v_and_b32_e32 v185, 0xffff0000, v176
	v_lshlrev_b32_e32 v184, 16, v176
	v_and_b32_e32 v187, 0xffff0000, v177
	v_lshlrev_b32_e32 v186, 16, v177
	v_and_b32_e32 v189, 0xffff0000, v178
	v_lshlrev_b32_e32 v188, 16, v178
	v_and_b32_e32 v131, 0xffff0000, v179
	v_lshlrev_b32_e32 v130, 16, v179
	v_add_f32_e32 v78, 1.0, v78
	v_add_f32_e32 v74, 1.0, v74
	v_add_f32_e32 v79, 1.0, v79
	v_add_f32_e32 v75, 1.0, v75
	v_add_f32_e32 v80, 1.0, v80
	v_add_f32_e32 v76, 1.0, v76
	v_add_f32_e32 v81, 1.0, v81
	v_add_f32_e32 v77, 1.0, v77
	v_rcp_f32_e32 v78, v78
	v_rcp_f32_e32 v74, v74
	v_rcp_f32_e32 v79, v79
	v_rcp_f32_e32 v75, v75
	v_rcp_f32_e32 v80, v80
	v_rcp_f32_e32 v76, v76
	v_rcp_f32_e32 v81, v81
	v_rcp_f32_e32 v77, v77
	v_pk_mul_f32 v[78:79], v[78:79], v[184:185]
	v_pk_mul_f32 v[80:81], v[80:81], v[186:187]
	v_pk_mul_f32 v[74:75], v[74:75], v[188:189]
	v_pk_mul_f32 v[76:77], v[76:77], v[130:131]
	v_cvt_pk_bf16_f32 v78, v78, v79
	v_cvt_pk_bf16_f32 v79, v80, v81
	v_cvt_pk_bf16_f32 v80, v74, v75
	v_cvt_pk_bf16_f32 v81, v76, v77
	global_store_dwordx4 v[150:151], v[78:81], off offset:512
	s_waitcnt vmcnt(15)
	v_pk_add_f32 v[72:73], v[72:73], v[142:143]
	v_pk_add_f32 v[70:71], v[70:71], v[140:141]
	v_pk_add_f32 v[68:69], v[68:69], v[146:147]
	v_pk_add_f32 v[66:67], v[66:67], v[144:145]
	v_mul_f32_e32 v70, 0xbfb8aa3b, v70
	v_mul_f32_e32 v66, 0xbfb8aa3b, v66
	v_mul_f32_e32 v71, 0xbfb8aa3b, v71
	v_mul_f32_e32 v67, 0xbfb8aa3b, v67
	v_mul_f32_e32 v72, 0xbfb8aa3b, v72
	v_mul_f32_e32 v68, 0xbfb8aa3b, v68
	v_mul_f32_e32 v73, 0xbfb8aa3b, v73
	v_mul_f32_e32 v69, 0xbfb8aa3b, v69
	v_exp_f32_e32 v70, v70
	v_exp_f32_e32 v66, v66
	v_exp_f32_e32 v71, v71
	v_exp_f32_e32 v67, v67
	v_exp_f32_e32 v72, v72
	v_exp_f32_e32 v68, v68
	v_exp_f32_e32 v73, v73
	v_exp_f32_e32 v69, v69
	v_and_b32_e32 v185, 0xffff0000, v180
	v_lshlrev_b32_e32 v184, 16, v180
	v_and_b32_e32 v187, 0xffff0000, v181
	v_lshlrev_b32_e32 v186, 16, v181
	v_and_b32_e32 v189, 0xffff0000, v182
	v_lshlrev_b32_e32 v188, 16, v182
	v_and_b32_e32 v131, 0xffff0000, v183
	v_lshlrev_b32_e32 v130, 16, v183
	v_add_f32_e32 v70, 1.0, v70
	v_add_f32_e32 v66, 1.0, v66
	v_add_f32_e32 v71, 1.0, v71
	v_add_f32_e32 v67, 1.0, v67
	v_add_f32_e32 v72, 1.0, v72
	v_add_f32_e32 v68, 1.0, v68
	v_add_f32_e32 v73, 1.0, v73
	v_add_f32_e32 v69, 1.0, v69
	v_rcp_f32_e32 v70, v70
	v_rcp_f32_e32 v66, v66
	v_rcp_f32_e32 v71, v71
	v_rcp_f32_e32 v67, v67
	v_rcp_f32_e32 v72, v72
	v_rcp_f32_e32 v68, v68
	v_rcp_f32_e32 v73, v73
	v_rcp_f32_e32 v69, v69
	v_pk_mul_f32 v[70:71], v[70:71], v[184:185]
	v_pk_mul_f32 v[72:73], v[72:73], v[186:187]
	v_pk_mul_f32 v[66:67], v[66:67], v[188:189]
	v_pk_mul_f32 v[68:69], v[68:69], v[130:131]
	v_cvt_pk_bf16_f32 v70, v70, v71
	v_cvt_pk_bf16_f32 v71, v72, v73
	v_cvt_pk_bf16_f32 v72, v66, v67
	v_cvt_pk_bf16_f32 v73, v68, v69
	global_store_dwordx4 v[150:151], v[70:73], off offset:768
	v_add_co_u32_e32 v150, vcc, 0x28000, v150
	s_nop 1
	v_addc_co_u32_e32 v151, vcc, 0, v151, vcc
	s_waitcnt vmcnt(11)
	v_pk_add_f32 v[64:65], v[64:65], v[134:135]
	v_pk_add_f32 v[62:63], v[62:63], v[132:133]
	v_pk_add_f32 v[60:61], v[60:61], v[138:139]
	v_pk_add_f32 v[58:59], v[58:59], v[136:137]
	v_mul_f32_e32 v62, 0xbfb8aa3b, v62
	v_mul_f32_e32 v58, 0xbfb8aa3b, v58
	v_mul_f32_e32 v63, 0xbfb8aa3b, v63
	v_mul_f32_e32 v59, 0xbfb8aa3b, v59
	v_mul_f32_e32 v64, 0xbfb8aa3b, v64
	v_mul_f32_e32 v60, 0xbfb8aa3b, v60
	v_mul_f32_e32 v65, 0xbfb8aa3b, v65
	v_mul_f32_e32 v61, 0xbfb8aa3b, v61
	v_exp_f32_e32 v62, v62
	v_exp_f32_e32 v58, v58
	v_exp_f32_e32 v63, v63
	v_exp_f32_e32 v59, v59
	v_exp_f32_e32 v64, v64
	v_exp_f32_e32 v60, v60
	v_exp_f32_e32 v65, v65
	v_exp_f32_e32 v61, v61
	v_and_b32_e32 v185, 0xffff0000, v98
	v_lshlrev_b32_e32 v184, 16, v98
	v_and_b32_e32 v187, 0xffff0000, v99
	v_lshlrev_b32_e32 v186, 16, v99
	v_and_b32_e32 v189, 0xffff0000, v100
	v_lshlrev_b32_e32 v188, 16, v100
	v_and_b32_e32 v131, 0xffff0000, v101
	v_lshlrev_b32_e32 v130, 16, v101
	v_add_f32_e32 v62, 1.0, v62
	v_add_f32_e32 v58, 1.0, v58
	v_add_f32_e32 v63, 1.0, v63
	v_add_f32_e32 v59, 1.0, v59
	v_add_f32_e32 v64, 1.0, v64
	v_add_f32_e32 v60, 1.0, v60
	v_add_f32_e32 v65, 1.0, v65
	v_add_f32_e32 v61, 1.0, v61
	v_rcp_f32_e32 v62, v62
	v_rcp_f32_e32 v58, v58
	v_rcp_f32_e32 v63, v63
	v_rcp_f32_e32 v59, v59
	v_rcp_f32_e32 v64, v64
	v_rcp_f32_e32 v60, v60
	v_rcp_f32_e32 v65, v65
	v_rcp_f32_e32 v61, v61
	v_pk_mul_f32 v[62:63], v[62:63], v[184:185]
	v_pk_mul_f32 v[64:65], v[64:65], v[186:187]
	v_pk_mul_f32 v[58:59], v[58:59], v[188:189]
	v_pk_mul_f32 v[60:61], v[60:61], v[130:131]
	v_cvt_pk_bf16_f32 v62, v62, v63
	v_cvt_pk_bf16_f32 v63, v64, v65
	v_cvt_pk_bf16_f32 v64, v58, v59
	v_cvt_pk_bf16_f32 v65, v60, v61
	global_store_dwordx4 v[150:151], v[62:65], off offset:512
	s_waitcnt vmcnt(11)
	v_pk_add_f32 v[56:57], v[56:57], v[142:143]
	v_pk_add_f32 v[54:55], v[54:55], v[140:141]
	v_pk_add_f32 v[52:53], v[52:53], v[146:147]
	v_pk_add_f32 v[50:51], v[50:51], v[144:145]
	v_mul_f32_e32 v54, 0xbfb8aa3b, v54
	v_mul_f32_e32 v50, 0xbfb8aa3b, v50
	v_mul_f32_e32 v55, 0xbfb8aa3b, v55
	v_mul_f32_e32 v51, 0xbfb8aa3b, v51
	v_mul_f32_e32 v56, 0xbfb8aa3b, v56
	v_mul_f32_e32 v52, 0xbfb8aa3b, v52
	v_mul_f32_e32 v57, 0xbfb8aa3b, v57
	v_mul_f32_e32 v53, 0xbfb8aa3b, v53
	v_exp_f32_e32 v54, v54
	v_exp_f32_e32 v50, v50
	v_exp_f32_e32 v55, v55
	v_exp_f32_e32 v51, v51
	v_exp_f32_e32 v56, v56
	v_exp_f32_e32 v52, v52
	v_exp_f32_e32 v57, v57
	v_exp_f32_e32 v53, v53
	v_and_b32_e32 v185, 0xffff0000, v102
	v_lshlrev_b32_e32 v184, 16, v102
	v_and_b32_e32 v187, 0xffff0000, v103
	v_lshlrev_b32_e32 v186, 16, v103
	v_and_b32_e32 v189, 0xffff0000, v104
	v_lshlrev_b32_e32 v188, 16, v104
	v_and_b32_e32 v131, 0xffff0000, v105
	v_lshlrev_b32_e32 v130, 16, v105
	v_add_f32_e32 v54, 1.0, v54
	v_add_f32_e32 v50, 1.0, v50
	v_add_f32_e32 v55, 1.0, v55
	v_add_f32_e32 v51, 1.0, v51
	v_add_f32_e32 v56, 1.0, v56
	v_add_f32_e32 v52, 1.0, v52
	v_add_f32_e32 v57, 1.0, v57
	v_add_f32_e32 v53, 1.0, v53
	v_rcp_f32_e32 v54, v54
	v_rcp_f32_e32 v50, v50
	v_rcp_f32_e32 v55, v55
	v_rcp_f32_e32 v51, v51
	v_rcp_f32_e32 v56, v56
	v_rcp_f32_e32 v52, v52
	v_rcp_f32_e32 v57, v57
	v_rcp_f32_e32 v53, v53
	v_pk_mul_f32 v[54:55], v[54:55], v[184:185]
	v_pk_mul_f32 v[56:57], v[56:57], v[186:187]
	v_pk_mul_f32 v[50:51], v[50:51], v[188:189]
	v_pk_mul_f32 v[52:53], v[52:53], v[130:131]
	v_cvt_pk_bf16_f32 v54, v54, v55
	v_cvt_pk_bf16_f32 v55, v56, v57
	v_cvt_pk_bf16_f32 v56, v50, v51
	v_cvt_pk_bf16_f32 v57, v52, v53
	global_store_dwordx4 v[150:151], v[54:57], off offset:768
	v_add_co_u32_e32 v150, vcc, 0x8000, v150
	s_nop 1
	v_addc_co_u32_e32 v151, vcc, 0, v151, vcc
	s_waitcnt vmcnt(11)
	v_pk_add_f32 v[48:49], v[48:49], v[134:135]
	v_pk_add_f32 v[46:47], v[46:47], v[132:133]
	v_pk_add_f32 v[44:45], v[44:45], v[138:139]
	v_pk_add_f32 v[42:43], v[42:43], v[136:137]
	v_mul_f32_e32 v46, 0xbfb8aa3b, v46
	v_mul_f32_e32 v42, 0xbfb8aa3b, v42
	v_mul_f32_e32 v47, 0xbfb8aa3b, v47
	v_mul_f32_e32 v43, 0xbfb8aa3b, v43
	v_mul_f32_e32 v48, 0xbfb8aa3b, v48
	v_mul_f32_e32 v44, 0xbfb8aa3b, v44
	v_mul_f32_e32 v49, 0xbfb8aa3b, v49
	v_mul_f32_e32 v45, 0xbfb8aa3b, v45
	v_exp_f32_e32 v46, v46
	v_exp_f32_e32 v42, v42
	v_exp_f32_e32 v47, v47
	v_exp_f32_e32 v43, v43
	v_exp_f32_e32 v48, v48
	v_exp_f32_e32 v44, v44
	v_exp_f32_e32 v49, v49
	v_exp_f32_e32 v45, v45
	v_and_b32_e32 v185, 0xffff0000, v106
	v_lshlrev_b32_e32 v184, 16, v106
	v_and_b32_e32 v187, 0xffff0000, v107
	v_lshlrev_b32_e32 v186, 16, v107
	v_and_b32_e32 v189, 0xffff0000, v108
	v_lshlrev_b32_e32 v188, 16, v108
	v_and_b32_e32 v131, 0xffff0000, v109
	v_lshlrev_b32_e32 v130, 16, v109
	v_add_f32_e32 v46, 1.0, v46
	v_add_f32_e32 v42, 1.0, v42
	v_add_f32_e32 v47, 1.0, v47
	v_add_f32_e32 v43, 1.0, v43
	v_add_f32_e32 v48, 1.0, v48
	v_add_f32_e32 v44, 1.0, v44
	v_add_f32_e32 v49, 1.0, v49
	v_add_f32_e32 v45, 1.0, v45
	v_rcp_f32_e32 v46, v46
	v_rcp_f32_e32 v42, v42
	v_rcp_f32_e32 v47, v47
	v_rcp_f32_e32 v43, v43
	v_rcp_f32_e32 v48, v48
	v_rcp_f32_e32 v44, v44
	v_rcp_f32_e32 v49, v49
	v_rcp_f32_e32 v45, v45
	v_pk_mul_f32 v[46:47], v[46:47], v[184:185]
	v_pk_mul_f32 v[48:49], v[48:49], v[186:187]
	v_pk_mul_f32 v[42:43], v[42:43], v[188:189]
	v_pk_mul_f32 v[44:45], v[44:45], v[130:131]
	v_cvt_pk_bf16_f32 v46, v46, v47
	v_cvt_pk_bf16_f32 v47, v48, v49
	v_cvt_pk_bf16_f32 v48, v42, v43
	v_cvt_pk_bf16_f32 v49, v44, v45
	global_store_dwordx4 v[150:151], v[46:49], off offset:512
	s_waitcnt vmcnt(11)
	v_pk_add_f32 v[40:41], v[40:41], v[142:143]
	v_pk_add_f32 v[38:39], v[38:39], v[140:141]
	v_pk_add_f32 v[36:37], v[36:37], v[146:147]
	v_pk_add_f32 v[34:35], v[34:35], v[144:145]
	v_mul_f32_e32 v38, 0xbfb8aa3b, v38
	v_mul_f32_e32 v34, 0xbfb8aa3b, v34
	v_mul_f32_e32 v39, 0xbfb8aa3b, v39
	v_mul_f32_e32 v35, 0xbfb8aa3b, v35
	v_mul_f32_e32 v40, 0xbfb8aa3b, v40
	v_mul_f32_e32 v36, 0xbfb8aa3b, v36
	v_mul_f32_e32 v41, 0xbfb8aa3b, v41
	v_mul_f32_e32 v37, 0xbfb8aa3b, v37
	v_exp_f32_e32 v38, v38
	v_exp_f32_e32 v34, v34
	v_exp_f32_e32 v39, v39
	v_exp_f32_e32 v35, v35
	v_exp_f32_e32 v40, v40
	v_exp_f32_e32 v36, v36
	v_exp_f32_e32 v41, v41
	v_exp_f32_e32 v37, v37
	v_and_b32_e32 v185, 0xffff0000, v110
	v_lshlrev_b32_e32 v184, 16, v110
	v_and_b32_e32 v187, 0xffff0000, v111
	v_lshlrev_b32_e32 v186, 16, v111
	v_and_b32_e32 v189, 0xffff0000, v112
	v_lshlrev_b32_e32 v188, 16, v112
	v_and_b32_e32 v131, 0xffff0000, v113
	v_lshlrev_b32_e32 v130, 16, v113
	v_add_f32_e32 v38, 1.0, v38
	v_add_f32_e32 v34, 1.0, v34
	v_add_f32_e32 v39, 1.0, v39
	v_add_f32_e32 v35, 1.0, v35
	v_add_f32_e32 v40, 1.0, v40
	v_add_f32_e32 v36, 1.0, v36
	v_add_f32_e32 v41, 1.0, v41
	v_add_f32_e32 v37, 1.0, v37
	v_rcp_f32_e32 v38, v38
	v_rcp_f32_e32 v34, v34
	v_rcp_f32_e32 v39, v39
	v_rcp_f32_e32 v35, v35
	v_rcp_f32_e32 v40, v40
	v_rcp_f32_e32 v36, v36
	v_rcp_f32_e32 v41, v41
	v_rcp_f32_e32 v37, v37
	v_pk_mul_f32 v[38:39], v[38:39], v[184:185]
	v_pk_mul_f32 v[40:41], v[40:41], v[186:187]
	v_pk_mul_f32 v[34:35], v[34:35], v[188:189]
	v_pk_mul_f32 v[36:37], v[36:37], v[130:131]
	v_cvt_pk_bf16_f32 v38, v38, v39
	v_cvt_pk_bf16_f32 v39, v40, v41
	v_cvt_pk_bf16_f32 v40, v34, v35
	v_cvt_pk_bf16_f32 v41, v36, v37
	global_store_dwordx4 v[150:151], v[38:41], off offset:768
	v_add_co_u32_e32 v150, vcc, 0x8000, v150
	s_nop 1
	v_addc_co_u32_e32 v151, vcc, 0, v151, vcc
	s_waitcnt vmcnt(11)
	v_pk_add_f32 v[32:33], v[32:33], v[134:135]
	v_pk_add_f32 v[30:31], v[30:31], v[132:133]
	v_pk_add_f32 v[28:29], v[28:29], v[138:139]
	v_pk_add_f32 v[26:27], v[26:27], v[136:137]
	v_mul_f32_e32 v30, 0xbfb8aa3b, v30
	v_mul_f32_e32 v26, 0xbfb8aa3b, v26
	v_mul_f32_e32 v31, 0xbfb8aa3b, v31
	v_mul_f32_e32 v27, 0xbfb8aa3b, v27
	v_mul_f32_e32 v32, 0xbfb8aa3b, v32
	v_mul_f32_e32 v28, 0xbfb8aa3b, v28
	v_mul_f32_e32 v33, 0xbfb8aa3b, v33
	v_mul_f32_e32 v29, 0xbfb8aa3b, v29
	v_exp_f32_e32 v30, v30
	v_exp_f32_e32 v26, v26
	v_exp_f32_e32 v31, v31
	v_exp_f32_e32 v27, v27
	v_exp_f32_e32 v32, v32
	v_exp_f32_e32 v28, v28
	v_exp_f32_e32 v33, v33
	v_exp_f32_e32 v29, v29
	v_and_b32_e32 v185, 0xffff0000, v114
	v_lshlrev_b32_e32 v184, 16, v114
	v_and_b32_e32 v187, 0xffff0000, v115
	v_lshlrev_b32_e32 v186, 16, v115
	v_and_b32_e32 v189, 0xffff0000, v116
	v_lshlrev_b32_e32 v188, 16, v116
	v_and_b32_e32 v131, 0xffff0000, v117
	v_lshlrev_b32_e32 v130, 16, v117
	v_add_f32_e32 v30, 1.0, v30
	v_add_f32_e32 v26, 1.0, v26
	v_add_f32_e32 v31, 1.0, v31
	v_add_f32_e32 v27, 1.0, v27
	v_add_f32_e32 v32, 1.0, v32
	v_add_f32_e32 v28, 1.0, v28
	v_add_f32_e32 v33, 1.0, v33
	v_add_f32_e32 v29, 1.0, v29
	v_rcp_f32_e32 v30, v30
	v_rcp_f32_e32 v26, v26
	v_rcp_f32_e32 v31, v31
	v_rcp_f32_e32 v27, v27
	v_rcp_f32_e32 v32, v32
	v_rcp_f32_e32 v28, v28
	v_rcp_f32_e32 v33, v33
	v_rcp_f32_e32 v29, v29
	v_pk_mul_f32 v[30:31], v[30:31], v[184:185]
	v_pk_mul_f32 v[32:33], v[32:33], v[186:187]
	v_pk_mul_f32 v[26:27], v[26:27], v[188:189]
	v_pk_mul_f32 v[28:29], v[28:29], v[130:131]
	v_cvt_pk_bf16_f32 v30, v30, v31
	v_cvt_pk_bf16_f32 v31, v32, v33
	v_cvt_pk_bf16_f32 v32, v26, v27
	v_cvt_pk_bf16_f32 v33, v28, v29
	global_store_dwordx4 v[150:151], v[30:33], off offset:512
	s_waitcnt vmcnt(11)
	v_pk_add_f32 v[24:25], v[24:25], v[142:143]
	v_pk_add_f32 v[22:23], v[22:23], v[140:141]
	v_pk_add_f32 v[20:21], v[20:21], v[146:147]
	v_pk_add_f32 v[18:19], v[18:19], v[144:145]
	v_mul_f32_e32 v22, 0xbfb8aa3b, v22
	v_mul_f32_e32 v18, 0xbfb8aa3b, v18
	v_mul_f32_e32 v23, 0xbfb8aa3b, v23
	v_mul_f32_e32 v19, 0xbfb8aa3b, v19
	v_mul_f32_e32 v24, 0xbfb8aa3b, v24
	v_mul_f32_e32 v20, 0xbfb8aa3b, v20
	v_mul_f32_e32 v25, 0xbfb8aa3b, v25
	v_mul_f32_e32 v21, 0xbfb8aa3b, v21
	v_exp_f32_e32 v22, v22
	v_exp_f32_e32 v18, v18
	v_exp_f32_e32 v23, v23
	v_exp_f32_e32 v19, v19
	v_exp_f32_e32 v24, v24
	v_exp_f32_e32 v20, v20
	v_exp_f32_e32 v25, v25
	v_exp_f32_e32 v21, v21
	v_and_b32_e32 v185, 0xffff0000, v118
	v_lshlrev_b32_e32 v184, 16, v118
	v_and_b32_e32 v187, 0xffff0000, v119
	v_lshlrev_b32_e32 v186, 16, v119
	v_and_b32_e32 v189, 0xffff0000, v120
	v_lshlrev_b32_e32 v188, 16, v120
	v_and_b32_e32 v131, 0xffff0000, v121
	v_lshlrev_b32_e32 v130, 16, v121
	v_add_f32_e32 v22, 1.0, v22
	v_add_f32_e32 v18, 1.0, v18
	v_add_f32_e32 v23, 1.0, v23
	v_add_f32_e32 v19, 1.0, v19
	v_add_f32_e32 v24, 1.0, v24
	v_add_f32_e32 v20, 1.0, v20
	v_add_f32_e32 v25, 1.0, v25
	v_add_f32_e32 v21, 1.0, v21
	v_rcp_f32_e32 v22, v22
	v_rcp_f32_e32 v18, v18
	v_rcp_f32_e32 v23, v23
	v_rcp_f32_e32 v19, v19
	v_rcp_f32_e32 v24, v24
	v_rcp_f32_e32 v20, v20
	v_rcp_f32_e32 v25, v25
	v_rcp_f32_e32 v21, v21
	v_pk_mul_f32 v[22:23], v[22:23], v[184:185]
	v_pk_mul_f32 v[24:25], v[24:25], v[186:187]
	v_pk_mul_f32 v[18:19], v[18:19], v[188:189]
	v_pk_mul_f32 v[20:21], v[20:21], v[130:131]
	v_cvt_pk_bf16_f32 v22, v22, v23
	v_cvt_pk_bf16_f32 v23, v24, v25
	v_cvt_pk_bf16_f32 v24, v18, v19
	v_cvt_pk_bf16_f32 v25, v20, v21
	global_store_dwordx4 v[150:151], v[22:25], off offset:768
	v_add_co_u32_e32 v150, vcc, 0x8000, v150
	s_nop 1
	v_addc_co_u32_e32 v151, vcc, 0, v151, vcc
	s_waitcnt vmcnt(11)
	v_pk_add_f32 v[16:17], v[16:17], v[134:135]
	v_pk_add_f32 v[14:15], v[14:15], v[132:133]
	v_pk_add_f32 v[12:13], v[12:13], v[138:139]
	v_pk_add_f32 v[10:11], v[10:11], v[136:137]
	v_mul_f32_e32 v14, 0xbfb8aa3b, v14
	v_mul_f32_e32 v10, 0xbfb8aa3b, v10
	v_mul_f32_e32 v15, 0xbfb8aa3b, v15
	v_mul_f32_e32 v11, 0xbfb8aa3b, v11
	v_mul_f32_e32 v16, 0xbfb8aa3b, v16
	v_mul_f32_e32 v12, 0xbfb8aa3b, v12
	v_mul_f32_e32 v17, 0xbfb8aa3b, v17
	v_mul_f32_e32 v13, 0xbfb8aa3b, v13
	v_exp_f32_e32 v14, v14
	v_exp_f32_e32 v10, v10
	v_exp_f32_e32 v15, v15
	v_exp_f32_e32 v11, v11
	v_exp_f32_e32 v16, v16
	v_exp_f32_e32 v12, v12
	v_exp_f32_e32 v17, v17
	v_exp_f32_e32 v13, v13
	v_and_b32_e32 v185, 0xffff0000, v122
	v_lshlrev_b32_e32 v184, 16, v122
	v_and_b32_e32 v187, 0xffff0000, v123
	v_lshlrev_b32_e32 v186, 16, v123
	v_and_b32_e32 v189, 0xffff0000, v124
	v_lshlrev_b32_e32 v188, 16, v124
	v_and_b32_e32 v131, 0xffff0000, v125
	v_lshlrev_b32_e32 v130, 16, v125
	v_add_f32_e32 v14, 1.0, v14
	v_add_f32_e32 v10, 1.0, v10
	v_add_f32_e32 v15, 1.0, v15
	v_add_f32_e32 v11, 1.0, v11
	v_add_f32_e32 v16, 1.0, v16
	v_add_f32_e32 v12, 1.0, v12
	v_add_f32_e32 v17, 1.0, v17
	v_add_f32_e32 v13, 1.0, v13
	v_rcp_f32_e32 v14, v14
	v_rcp_f32_e32 v10, v10
	v_rcp_f32_e32 v15, v15
	v_rcp_f32_e32 v11, v11
	v_rcp_f32_e32 v16, v16
	v_rcp_f32_e32 v12, v12
	v_rcp_f32_e32 v17, v17
	v_rcp_f32_e32 v13, v13
	v_pk_mul_f32 v[14:15], v[14:15], v[184:185]
	v_pk_mul_f32 v[16:17], v[16:17], v[186:187]
	v_pk_mul_f32 v[10:11], v[10:11], v[188:189]
	v_pk_mul_f32 v[12:13], v[12:13], v[130:131]
	v_cvt_pk_bf16_f32 v14, v14, v15
	v_cvt_pk_bf16_f32 v15, v16, v17
	v_cvt_pk_bf16_f32 v16, v10, v11
	v_cvt_pk_bf16_f32 v17, v12, v13
	global_store_dwordx4 v[150:151], v[14:17], off offset:512
	s_waitcnt vmcnt(11)
	v_pk_add_f32 v[8:9], v[8:9], v[142:143]
	v_pk_add_f32 v[6:7], v[6:7], v[140:141]
	v_pk_add_f32 v[4:5], v[4:5], v[146:147]
	v_pk_add_f32 v[2:3], v[2:3], v[144:145]
	v_mul_f32_e32 v6, 0xbfb8aa3b, v6
	v_mul_f32_e32 v2, 0xbfb8aa3b, v2
	v_mul_f32_e32 v7, 0xbfb8aa3b, v7
	v_mul_f32_e32 v3, 0xbfb8aa3b, v3
	v_mul_f32_e32 v8, 0xbfb8aa3b, v8
	v_mul_f32_e32 v4, 0xbfb8aa3b, v4
	v_mul_f32_e32 v9, 0xbfb8aa3b, v9
	v_mul_f32_e32 v5, 0xbfb8aa3b, v5
	v_exp_f32_e32 v6, v6
	v_exp_f32_e32 v2, v2
	v_exp_f32_e32 v7, v7
	v_exp_f32_e32 v3, v3
	v_exp_f32_e32 v8, v8
	v_exp_f32_e32 v4, v4
	v_exp_f32_e32 v9, v9
	v_exp_f32_e32 v5, v5
	v_and_b32_e32 v185, 0xffff0000, v126
	v_lshlrev_b32_e32 v184, 16, v126
	v_and_b32_e32 v187, 0xffff0000, v127
	v_lshlrev_b32_e32 v186, 16, v127
	v_and_b32_e32 v189, 0xffff0000, v128
	v_lshlrev_b32_e32 v188, 16, v128
	v_and_b32_e32 v131, 0xffff0000, v129
	v_lshlrev_b32_e32 v130, 16, v129
	v_add_f32_e32 v6, 1.0, v6
	v_add_f32_e32 v2, 1.0, v2
	v_add_f32_e32 v7, 1.0, v7
	v_add_f32_e32 v3, 1.0, v3
	v_add_f32_e32 v8, 1.0, v8
	v_add_f32_e32 v4, 1.0, v4
	v_add_f32_e32 v9, 1.0, v9
	v_add_f32_e32 v5, 1.0, v5
	v_rcp_f32_e32 v6, v6
	v_rcp_f32_e32 v2, v2
	v_rcp_f32_e32 v7, v7
	v_rcp_f32_e32 v3, v3
	v_rcp_f32_e32 v8, v8
	v_rcp_f32_e32 v4, v4
	v_rcp_f32_e32 v9, v9
	v_rcp_f32_e32 v5, v5
	v_pk_mul_f32 v[6:7], v[6:7], v[184:185]
	v_pk_mul_f32 v[8:9], v[8:9], v[186:187]
	v_pk_mul_f32 v[2:3], v[2:3], v[188:189]
	v_pk_mul_f32 v[4:5], v[4:5], v[130:131]
	v_cvt_pk_bf16_f32 v6, v6, v7
	v_cvt_pk_bf16_f32 v7, v8, v9
	v_cvt_pk_bf16_f32 v8, v2, v3
	v_cvt_pk_bf16_f32 v9, v4, v5
	global_store_dwordx4 v[150:151], v[6:9], off offset:768
	s_waitcnt vmcnt(0)
	s_cbranch_scc0 .LBB0_738
	s_barrier
